# sc_conv_rewrite_strips
# speedup vs baseline: 1.1012x; 1.0518x over previous
.LBB0_974:
	s_or_b64 exec, exec, s[0:1]
	s_waitcnt lgkmcnt(0)
	v_mov_b32_e32 v0, v210
	v_mov_b32_e32 v2, v210
	v_readlane_b32 s0, v254, 1
	s_barrier
	v_and_b32_e32 v1, 0x7f, v210
	v_lshrrev_b32_e32 v2, 7, v210
	v_lshlrev_b32_e32 v1, 4, v1
	v_readlane_b32 s54, v253, 34
	v_readlane_b32 s55, v253, 35
	v_add_u32_e32 v0, 0x800, v1
	v_readfirstlane_b32 s0, v2
	v_lshlrev_b32_e32 v2, 1, v1
	s_lshl_b32 s1, s94, 2
	s_add_i32 s1, s1, s0
	s_mul_i32 s6, s1, 0x60000
	s_add_u32 s2, s92, s6
	s_addc_u32 s3, s93, 0
	s_lshl_b32 s6, s1, 17
	s_add_u32 s18, s90, s6
	s_addc_u32 s19, s91, 0
	v_add_u32_e32 v3, 0x1000, v2
	v_add_u32_e32 v4, 0x2000, v2
	s_mov_b32 s7, 0xffff0000
	global_load_dwordx4 v[8:11], v2, s[54:55]
	global_load_dwordx4 v[12:15], v2, s[54:55] offset:16
	global_load_dwordx4 v[16:19], v3, s[54:55]
	global_load_dwordx4 v[20:23], v3, s[54:55] offset:16
	global_load_dwordx4 v[24:27], v4, s[54:55]
	global_load_dwordx4 v[28:31], v4, s[54:55] offset:16
	s_and_b32 s6, s1, 63
	s_cmp_eq_u32 s6, 0
	s_cbranch_scc1 .Lsc_pzero
	s_sub_u32 s8, s2, 0x3000
	s_subb_u32 s9, s3, 0
	global_load_dwordx4 v[72:75], v0, s[8:9]
	global_load_dwordx4 v[76:79], v0, s[8:9] offset:2048
	s_add_u32 s8, s8, 0x1800
	s_addc_u32 s9, s9, 0
	global_load_dwordx4 v[84:87], v0, s[8:9]
	global_load_dwordx4 v[88:91], v0, s[8:9] offset:2048
	s_waitcnt vmcnt(0)
	v_lshlrev_b32_e32 v48, 16, v72
	v_and_b32_e32 v49, s7, v72
	v_lshlrev_b32_e32 v56, 16, v76
	v_and_b32_e32 v57, s7, v76
	v_lshlrev_b32_e32 v50, 16, v73
	v_and_b32_e32 v51, s7, v73
	v_lshlrev_b32_e32 v58, 16, v77
	v_and_b32_e32 v59, s7, v77
	v_lshlrev_b32_e32 v52, 16, v74
	v_and_b32_e32 v53, s7, v74
	v_lshlrev_b32_e32 v60, 16, v78
	v_and_b32_e32 v61, s7, v78
	v_lshlrev_b32_e32 v54, 16, v75
	v_and_b32_e32 v55, s7, v75
	v_lshlrev_b32_e32 v62, 16, v79
	v_and_b32_e32 v63, s7, v79
	v_pk_mul_f32 v[48:49], v[56:57], v[48:49]
	v_pk_mul_f32 v[50:51], v[58:59], v[50:51]
	v_pk_mul_f32 v[52:53], v[60:61], v[52:53]
	v_pk_mul_f32 v[54:55], v[62:63], v[54:55]
	v_cvt_pk_bf16_f32 v48, v48, v49
	v_cvt_pk_bf16_f32 v50, v50, v51
	v_cvt_pk_bf16_f32 v52, v52, v53
	v_cvt_pk_bf16_f32 v54, v54, v55
	v_and_b32_e32 v33, s7, v48
	v_lshlrev_b32_e32 v32, 16, v48
	v_and_b32_e32 v35, s7, v50
	v_lshlrev_b32_e32 v34, 16, v50
	v_and_b32_e32 v37, s7, v52
	v_lshlrev_b32_e32 v36, 16, v52
	v_and_b32_e32 v39, s7, v54
	v_lshlrev_b32_e32 v38, 16, v54
	v_lshlrev_b32_e32 v48, 16, v84
	v_and_b32_e32 v49, s7, v84
	v_lshlrev_b32_e32 v56, 16, v88
	v_and_b32_e32 v57, s7, v88
	v_lshlrev_b32_e32 v50, 16, v85
	v_and_b32_e32 v51, s7, v85
	v_lshlrev_b32_e32 v58, 16, v89
	v_and_b32_e32 v59, s7, v89
	v_lshlrev_b32_e32 v52, 16, v86
	v_and_b32_e32 v53, s7, v86
	v_lshlrev_b32_e32 v60, 16, v90
	v_and_b32_e32 v61, s7, v90
	v_lshlrev_b32_e32 v54, 16, v87
	v_and_b32_e32 v55, s7, v87
	v_lshlrev_b32_e32 v62, 16, v91
	v_and_b32_e32 v63, s7, v91
	v_pk_mul_f32 v[48:49], v[56:57], v[48:49]
	v_pk_mul_f32 v[50:51], v[58:59], v[50:51]
	v_pk_mul_f32 v[52:53], v[60:61], v[52:53]
	v_pk_mul_f32 v[54:55], v[62:63], v[54:55]
	v_cvt_pk_bf16_f32 v48, v48, v49
	v_cvt_pk_bf16_f32 v50, v50, v51
	v_cvt_pk_bf16_f32 v52, v52, v53
	v_cvt_pk_bf16_f32 v54, v54, v55
	v_and_b32_e32 v41, s7, v48
	v_lshlrev_b32_e32 v40, 16, v48
	v_and_b32_e32 v43, s7, v50
	v_lshlrev_b32_e32 v42, 16, v50
	v_and_b32_e32 v45, s7, v52
	v_lshlrev_b32_e32 v44, 16, v52
	v_and_b32_e32 v47, s7, v54
	v_lshlrev_b32_e32 v46, 16, v54
	s_branch .Lsc_pdone
.Lsc_pzero:
	v_mov_b32_e32 v32, 0
	v_mov_b32_e32 v33, 0
	v_mov_b32_e32 v34, 0
	v_mov_b32_e32 v35, 0
	v_mov_b32_e32 v36, 0
	v_mov_b32_e32 v37, 0
	v_mov_b32_e32 v38, 0
	v_mov_b32_e32 v39, 0
	v_mov_b32_e32 v40, 0
	v_mov_b32_e32 v41, 0
	v_mov_b32_e32 v42, 0
	v_mov_b32_e32 v43, 0
	v_mov_b32_e32 v44, 0
	v_mov_b32_e32 v45, 0
	v_mov_b32_e32 v46, 0
	v_mov_b32_e32 v47, 0
.Lsc_pdone:
	s_mov_b32 s6, 8
	global_load_dwordx4 v[72:75], v0, s[2:3]
	global_load_dwordx4 v[76:79], v0, s[2:3] offset:2048
	global_load_dwordx4 v[80:83], v0, s[2:3] offset:-2048
	s_add_u32 s2, s2, 0x1800
	s_addc_u32 s3, s3, 0
	global_load_dwordx4 v[84:87], v0, s[2:3]
	global_load_dwordx4 v[88:91], v0, s[2:3] offset:2048
	global_load_dwordx4 v[92:95], v0, s[2:3] offset:-2048
	s_add_u32 s2, s2, 0x1800
	s_addc_u32 s3, s3, 0
	global_load_dwordx4 v[96:99], v0, s[2:3]
	global_load_dwordx4 v[100:103], v0, s[2:3] offset:2048
	global_load_dwordx4 v[104:107], v0, s[2:3] offset:-2048
	s_add_u32 s2, s2, 0x1800
	s_addc_u32 s3, s3, 0
	global_load_dwordx4 v[108:111], v0, s[2:3]
	global_load_dwordx4 v[112:115], v0, s[2:3] offset:2048
	global_load_dwordx4 v[116:119], v0, s[2:3] offset:-2048
	s_add_u32 s2, s2, 0x1800
	s_addc_u32 s3, s3, 0
	global_load_dwordx4 v[120:123], v0, s[2:3]
	global_load_dwordx4 v[124:127], v0, s[2:3] offset:2048
	global_load_dwordx4 v[128:131], v0, s[2:3] offset:-2048
	s_add_u32 s2, s2, 0x1800
	s_addc_u32 s3, s3, 0
	global_load_dwordx4 v[132:135], v0, s[2:3]
	global_load_dwordx4 v[136:139], v0, s[2:3] offset:2048
	global_load_dwordx4 v[140:143], v0, s[2:3] offset:-2048
	s_add_u32 s2, s2, 0x1800
	s_addc_u32 s3, s3, 0
	global_load_dwordx4 v[144:147], v0, s[2:3]
	global_load_dwordx4 v[148:151], v0, s[2:3] offset:2048
	global_load_dwordx4 v[152:155], v0, s[2:3] offset:-2048
	s_add_u32 s2, s2, 0x1800
	s_addc_u32 s3, s3, 0
	global_load_dwordx4 v[156:159], v0, s[2:3]
	global_load_dwordx4 v[160:163], v0, s[2:3] offset:2048
	global_load_dwordx4 v[164:167], v0, s[2:3] offset:-2048
	s_add_u32 s2, s2, 0x1800
	s_addc_u32 s3, s3, 0
	s_waitcnt vmcnt(12)
.Lsc_loop:
	v_lshlrev_b32_e32 v48, 16, v72
	v_and_b32_e32 v49, s7, v72
	v_lshlrev_b32_e32 v56, 16, v76
	v_and_b32_e32 v57, s7, v76
	v_lshlrev_b32_e32 v50, 16, v73
	v_and_b32_e32 v51, s7, v73
	v_lshlrev_b32_e32 v58, 16, v77
	v_and_b32_e32 v59, s7, v77
	v_lshlrev_b32_e32 v52, 16, v74
	v_and_b32_e32 v53, s7, v74
	v_lshlrev_b32_e32 v60, 16, v78
	v_and_b32_e32 v61, s7, v78
	v_lshlrev_b32_e32 v54, 16, v75
	v_and_b32_e32 v55, s7, v75
	v_lshlrev_b32_e32 v62, 16, v79
	v_and_b32_e32 v63, s7, v79
	v_pk_mul_f32 v[48:49], v[56:57], v[48:49]
	v_pk_mul_f32 v[50:51], v[58:59], v[50:51]
	v_pk_mul_f32 v[52:53], v[60:61], v[52:53]
	v_pk_mul_f32 v[54:55], v[62:63], v[54:55]
	v_cvt_pk_bf16_f32 v48, v48, v49
	v_cvt_pk_bf16_f32 v50, v50, v51
	v_cvt_pk_bf16_f32 v52, v52, v53
	v_cvt_pk_bf16_f32 v54, v54, v55
	v_and_b32_e32 v73, s7, v48
	v_lshlrev_b32_e32 v72, 16, v48
	v_and_b32_e32 v75, s7, v50
	v_lshlrev_b32_e32 v74, 16, v50
	v_and_b32_e32 v77, s7, v52
	v_lshlrev_b32_e32 v76, 16, v52
	v_and_b32_e32 v79, s7, v54
	v_lshlrev_b32_e32 v78, 16, v54
	v_pk_fma_f32 v[56:57], v[8:9], v[32:33], 0 op_sel_hi:[1,1,0]
	v_pk_fma_f32 v[58:59], v[10:11], v[34:35], 0 op_sel_hi:[1,1,0]
	v_pk_fma_f32 v[60:61], v[12:13], v[36:37], 0 op_sel_hi:[1,1,0]
	v_pk_fma_f32 v[62:63], v[14:15], v[38:39], 0 op_sel_hi:[1,1,0]
	v_lshlrev_b32_e32 v48, 16, v80
	v_and_b32_e32 v49, s7, v80
	v_lshlrev_b32_e32 v50, 16, v81
	v_and_b32_e32 v51, s7, v81
	v_lshlrev_b32_e32 v52, 16, v82
	v_and_b32_e32 v53, s7, v82
	v_lshlrev_b32_e32 v54, 16, v83
	v_and_b32_e32 v55, s7, v83
	v_pk_fma_f32 v[56:57], v[16:17], v[40:41], v[56:57]
	v_pk_fma_f32 v[58:59], v[18:19], v[42:43], v[58:59]
	v_pk_fma_f32 v[60:61], v[20:21], v[44:45], v[60:61]
	v_pk_fma_f32 v[62:63], v[22:23], v[46:47], v[62:63]
	v_pk_fma_f32 v[56:57], v[24:25], v[72:73], v[56:57]
	v_pk_fma_f32 v[58:59], v[26:27], v[74:75], v[58:59]
	v_pk_fma_f32 v[60:61], v[28:29], v[76:77], v[60:61]
	v_pk_fma_f32 v[62:63], v[30:31], v[78:79], v[62:63]
	v_pk_mul_f32 v[48:49], v[56:57], v[48:49]
	v_pk_mul_f32 v[50:51], v[58:59], v[50:51]
	v_pk_mul_f32 v[52:53], v[60:61], v[52:53]
	v_pk_mul_f32 v[54:55], v[62:63], v[54:55]
	v_cvt_pk_bf16_f32 v64, v48, v49
	v_cvt_pk_bf16_f32 v65, v50, v51
	v_cvt_pk_bf16_f32 v66, v52, v53
	v_cvt_pk_bf16_f32 v67, v54, v55
	global_store_dwordx4 v1, v[64:67], s[18:19]
	s_add_u32 s18, s18, 0x800
	s_addc_u32 s19, s19, 0
	v_lshlrev_b32_e32 v48, 16, v84
	v_and_b32_e32 v49, s7, v84
	v_lshlrev_b32_e32 v56, 16, v88
	v_and_b32_e32 v57, s7, v88
	v_lshlrev_b32_e32 v50, 16, v85
	v_and_b32_e32 v51, s7, v85
	v_lshlrev_b32_e32 v58, 16, v89
	v_and_b32_e32 v59, s7, v89
	v_lshlrev_b32_e32 v52, 16, v86
	v_and_b32_e32 v53, s7, v86
	v_lshlrev_b32_e32 v60, 16, v90
	v_and_b32_e32 v61, s7, v90
	v_lshlrev_b32_e32 v54, 16, v87
	v_and_b32_e32 v55, s7, v87
	v_lshlrev_b32_e32 v62, 16, v91
	v_and_b32_e32 v63, s7, v91
	v_pk_mul_f32 v[48:49], v[56:57], v[48:49]
	v_pk_mul_f32 v[50:51], v[58:59], v[50:51]
	v_pk_mul_f32 v[52:53], v[60:61], v[52:53]
	v_pk_mul_f32 v[54:55], v[62:63], v[54:55]
	v_cvt_pk_bf16_f32 v48, v48, v49
	v_cvt_pk_bf16_f32 v50, v50, v51
	v_cvt_pk_bf16_f32 v52, v52, v53
	v_cvt_pk_bf16_f32 v54, v54, v55
	v_and_b32_e32 v85, s7, v48
	v_lshlrev_b32_e32 v84, 16, v48
	v_and_b32_e32 v87, s7, v50
	v_lshlrev_b32_e32 v86, 16, v50
	v_and_b32_e32 v89, s7, v52
	v_lshlrev_b32_e32 v88, 16, v52
	v_and_b32_e32 v91, s7, v54
	v_lshlrev_b32_e32 v90, 16, v54
	v_pk_fma_f32 v[56:57], v[8:9], v[40:41], 0 op_sel_hi:[1,1,0]
	v_pk_fma_f32 v[58:59], v[10:11], v[42:43], 0 op_sel_hi:[1,1,0]
	v_pk_fma_f32 v[60:61], v[12:13], v[44:45], 0 op_sel_hi:[1,1,0]
	v_pk_fma_f32 v[62:63], v[14:15], v[46:47], 0 op_sel_hi:[1,1,0]
	v_lshlrev_b32_e32 v48, 16, v92
	v_and_b32_e32 v49, s7, v92
	v_lshlrev_b32_e32 v50, 16, v93
	v_and_b32_e32 v51, s7, v93
	v_lshlrev_b32_e32 v52, 16, v94
	v_and_b32_e32 v53, s7, v94
	v_lshlrev_b32_e32 v54, 16, v95
	v_and_b32_e32 v55, s7, v95
	v_pk_fma_f32 v[56:57], v[16:17], v[72:73], v[56:57]
	v_pk_fma_f32 v[58:59], v[18:19], v[74:75], v[58:59]
	v_pk_fma_f32 v[60:61], v[20:21], v[76:77], v[60:61]
	v_pk_fma_f32 v[62:63], v[22:23], v[78:79], v[62:63]
	v_pk_fma_f32 v[56:57], v[24:25], v[84:85], v[56:57]
	v_pk_fma_f32 v[58:59], v[26:27], v[86:87], v[58:59]
	v_pk_fma_f32 v[60:61], v[28:29], v[88:89], v[60:61]
	v_pk_fma_f32 v[62:63], v[30:31], v[90:91], v[62:63]
	v_pk_mul_f32 v[48:49], v[56:57], v[48:49]
	v_pk_mul_f32 v[50:51], v[58:59], v[50:51]
	v_pk_mul_f32 v[52:53], v[60:61], v[52:53]
	v_pk_mul_f32 v[54:55], v[62:63], v[54:55]
	v_cvt_pk_bf16_f32 v68, v48, v49
	v_cvt_pk_bf16_f32 v69, v50, v51
	v_cvt_pk_bf16_f32 v70, v52, v53
	v_cvt_pk_bf16_f32 v71, v54, v55
	global_store_dwordx4 v1, v[68:71], s[18:19]
	s_add_u32 s18, s18, 0x800
	s_addc_u32 s19, s19, 0
	v_lshlrev_b32_e32 v48, 16, v96
	v_and_b32_e32 v49, s7, v96
	v_lshlrev_b32_e32 v56, 16, v100
	v_and_b32_e32 v57, s7, v100
	v_lshlrev_b32_e32 v50, 16, v97
	v_and_b32_e32 v51, s7, v97
	v_lshlrev_b32_e32 v58, 16, v101
	v_and_b32_e32 v59, s7, v101
	v_lshlrev_b32_e32 v52, 16, v98
	v_and_b32_e32 v53, s7, v98
	v_lshlrev_b32_e32 v60, 16, v102
	v_and_b32_e32 v61, s7, v102
	v_lshlrev_b32_e32 v54, 16, v99
	v_and_b32_e32 v55, s7, v99
	v_lshlrev_b32_e32 v62, 16, v103
	v_and_b32_e32 v63, s7, v103
	v_pk_mul_f32 v[48:49], v[56:57], v[48:49]
	v_pk_mul_f32 v[50:51], v[58:59], v[50:51]
	v_pk_mul_f32 v[52:53], v[60:61], v[52:53]
	v_pk_mul_f32 v[54:55], v[62:63], v[54:55]
	v_cvt_pk_bf16_f32 v48, v48, v49
	v_cvt_pk_bf16_f32 v50, v50, v51
	v_cvt_pk_bf16_f32 v52, v52, v53
	v_cvt_pk_bf16_f32 v54, v54, v55
	v_and_b32_e32 v33, s7, v48
	v_lshlrev_b32_e32 v32, 16, v48
	v_and_b32_e32 v35, s7, v50
	v_lshlrev_b32_e32 v34, 16, v50
	v_and_b32_e32 v37, s7, v52
	v_lshlrev_b32_e32 v36, 16, v52
	v_and_b32_e32 v39, s7, v54
	v_lshlrev_b32_e32 v38, 16, v54
	v_pk_fma_f32 v[56:57], v[8:9], v[72:73], 0 op_sel_hi:[1,1,0]
	v_pk_fma_f32 v[58:59], v[10:11], v[74:75], 0 op_sel_hi:[1,1,0]
	v_pk_fma_f32 v[60:61], v[12:13], v[76:77], 0 op_sel_hi:[1,1,0]
	v_pk_fma_f32 v[62:63], v[14:15], v[78:79], 0 op_sel_hi:[1,1,0]
	v_lshlrev_b32_e32 v48, 16, v104
	v_and_b32_e32 v49, s7, v104
	v_lshlrev_b32_e32 v50, 16, v105
	v_and_b32_e32 v51, s7, v105
	v_lshlrev_b32_e32 v52, 16, v106
	v_and_b32_e32 v53, s7, v106
	v_lshlrev_b32_e32 v54, 16, v107
	v_and_b32_e32 v55, s7, v107
	v_pk_fma_f32 v[56:57], v[16:17], v[84:85], v[56:57]
	v_pk_fma_f32 v[58:59], v[18:19], v[86:87], v[58:59]
	v_pk_fma_f32 v[60:61], v[20:21], v[88:89], v[60:61]
	v_pk_fma_f32 v[62:63], v[22:23], v[90:91], v[62:63]
	v_pk_fma_f32 v[56:57], v[24:25], v[32:33], v[56:57]
	v_pk_fma_f32 v[58:59], v[26:27], v[34:35], v[58:59]
	v_pk_fma_f32 v[60:61], v[28:29], v[36:37], v[60:61]
	v_pk_fma_f32 v[62:63], v[30:31], v[38:39], v[62:63]
	v_pk_mul_f32 v[48:49], v[56:57], v[48:49]
	v_pk_mul_f32 v[50:51], v[58:59], v[50:51]
	v_pk_mul_f32 v[52:53], v[60:61], v[52:53]
	v_pk_mul_f32 v[54:55], v[62:63], v[54:55]
	v_cvt_pk_bf16_f32 v64, v48, v49
	v_cvt_pk_bf16_f32 v65, v50, v51
	v_cvt_pk_bf16_f32 v66, v52, v53
	v_cvt_pk_bf16_f32 v67, v54, v55
	global_store_dwordx4 v1, v[64:67], s[18:19]
	s_add_u32 s18, s18, 0x800
	s_addc_u32 s19, s19, 0
	v_lshlrev_b32_e32 v48, 16, v108
	v_and_b32_e32 v49, s7, v108
	v_lshlrev_b32_e32 v56, 16, v112
	v_and_b32_e32 v57, s7, v112
	v_lshlrev_b32_e32 v50, 16, v109
	v_and_b32_e32 v51, s7, v109
	v_lshlrev_b32_e32 v58, 16, v113
	v_and_b32_e32 v59, s7, v113
	v_lshlrev_b32_e32 v52, 16, v110
	v_and_b32_e32 v53, s7, v110
	v_lshlrev_b32_e32 v60, 16, v114
	v_and_b32_e32 v61, s7, v114
	v_lshlrev_b32_e32 v54, 16, v111
	v_and_b32_e32 v55, s7, v111
	v_lshlrev_b32_e32 v62, 16, v115
	v_and_b32_e32 v63, s7, v115
	v_pk_mul_f32 v[48:49], v[56:57], v[48:49]
	v_pk_mul_f32 v[50:51], v[58:59], v[50:51]
	v_pk_mul_f32 v[52:53], v[60:61], v[52:53]
	v_pk_mul_f32 v[54:55], v[62:63], v[54:55]
	v_cvt_pk_bf16_f32 v48, v48, v49
	v_cvt_pk_bf16_f32 v50, v50, v51
	v_cvt_pk_bf16_f32 v52, v52, v53
	v_cvt_pk_bf16_f32 v54, v54, v55
	v_and_b32_e32 v41, s7, v48
	v_lshlrev_b32_e32 v40, 16, v48
	v_and_b32_e32 v43, s7, v50
	v_lshlrev_b32_e32 v42, 16, v50
	v_and_b32_e32 v45, s7, v52
	v_lshlrev_b32_e32 v44, 16, v52
	v_and_b32_e32 v47, s7, v54
	v_lshlrev_b32_e32 v46, 16, v54
	v_pk_fma_f32 v[56:57], v[8:9], v[84:85], 0 op_sel_hi:[1,1,0]
	v_pk_fma_f32 v[58:59], v[10:11], v[86:87], 0 op_sel_hi:[1,1,0]
	v_pk_fma_f32 v[60:61], v[12:13], v[88:89], 0 op_sel_hi:[1,1,0]
	v_pk_fma_f32 v[62:63], v[14:15], v[90:91], 0 op_sel_hi:[1,1,0]
	v_lshlrev_b32_e32 v48, 16, v116
	v_and_b32_e32 v49, s7, v116
	v_lshlrev_b32_e32 v50, 16, v117
	v_and_b32_e32 v51, s7, v117
	v_lshlrev_b32_e32 v52, 16, v118
	v_and_b32_e32 v53, s7, v118
	v_lshlrev_b32_e32 v54, 16, v119
	v_and_b32_e32 v55, s7, v119
	v_pk_fma_f32 v[56:57], v[16:17], v[32:33], v[56:57]
	v_pk_fma_f32 v[58:59], v[18:19], v[34:35], v[58:59]
	v_pk_fma_f32 v[60:61], v[20:21], v[36:37], v[60:61]
	v_pk_fma_f32 v[62:63], v[22:23], v[38:39], v[62:63]
	v_pk_fma_f32 v[56:57], v[24:25], v[40:41], v[56:57]
	v_pk_fma_f32 v[58:59], v[26:27], v[42:43], v[58:59]
	v_pk_fma_f32 v[60:61], v[28:29], v[44:45], v[60:61]
	v_pk_fma_f32 v[62:63], v[30:31], v[46:47], v[62:63]
	v_pk_mul_f32 v[48:49], v[56:57], v[48:49]
	v_pk_mul_f32 v[50:51], v[58:59], v[50:51]
	v_pk_mul_f32 v[52:53], v[60:61], v[52:53]
	v_pk_mul_f32 v[54:55], v[62:63], v[54:55]
	v_cvt_pk_bf16_f32 v68, v48, v49
	v_cvt_pk_bf16_f32 v69, v50, v51
	v_cvt_pk_bf16_f32 v70, v52, v53
	v_cvt_pk_bf16_f32 v71, v54, v55
	global_store_dwordx4 v1, v[68:71], s[18:19]
	s_add_u32 s18, s18, 0x800
	s_addc_u32 s19, s19, 0
	s_cmp_eq_u32 s6, 1
	s_cbranch_scc1 .Lsc_lastA
	global_load_dwordx4 v[72:75], v0, s[2:3]
	global_load_dwordx4 v[76:79], v0, s[2:3] offset:2048
	global_load_dwordx4 v[80:83], v0, s[2:3] offset:-2048
	s_add_u32 s2, s2, 0x1800
	s_addc_u32 s3, s3, 0
	global_load_dwordx4 v[84:87], v0, s[2:3]
	global_load_dwordx4 v[88:91], v0, s[2:3] offset:2048
	global_load_dwordx4 v[92:95], v0, s[2:3] offset:-2048
	s_add_u32 s2, s2, 0x1800
	s_addc_u32 s3, s3, 0
	global_load_dwordx4 v[96:99], v0, s[2:3]
	global_load_dwordx4 v[100:103], v0, s[2:3] offset:2048
	global_load_dwordx4 v[104:107], v0, s[2:3] offset:-2048
	s_add_u32 s2, s2, 0x1800
	s_addc_u32 s3, s3, 0
	global_load_dwordx4 v[108:111], v0, s[2:3]
	global_load_dwordx4 v[112:115], v0, s[2:3] offset:2048
	global_load_dwordx4 v[116:119], v0, s[2:3] offset:-2048
	s_add_u32 s2, s2, 0x1800
	s_addc_u32 s3, s3, 0
	s_waitcnt vmcnt(16)
	s_branch .Lsc_doB
.Lsc_lastA:
	s_waitcnt vmcnt(4)
.Lsc_doB:
	v_lshlrev_b32_e32 v48, 16, v120
	v_and_b32_e32 v49, s7, v120
	v_lshlrev_b32_e32 v56, 16, v124
	v_and_b32_e32 v57, s7, v124
	v_lshlrev_b32_e32 v50, 16, v121
	v_and_b32_e32 v51, s7, v121
	v_lshlrev_b32_e32 v58, 16, v125
	v_and_b32_e32 v59, s7, v125
	v_lshlrev_b32_e32 v52, 16, v122
	v_and_b32_e32 v53, s7, v122
	v_lshlrev_b32_e32 v60, 16, v126
	v_and_b32_e32 v61, s7, v126
	v_lshlrev_b32_e32 v54, 16, v123
	v_and_b32_e32 v55, s7, v123
	v_lshlrev_b32_e32 v62, 16, v127
	v_and_b32_e32 v63, s7, v127
	v_pk_mul_f32 v[48:49], v[56:57], v[48:49]
	v_pk_mul_f32 v[50:51], v[58:59], v[50:51]
	v_pk_mul_f32 v[52:53], v[60:61], v[52:53]
	v_pk_mul_f32 v[54:55], v[62:63], v[54:55]
	v_cvt_pk_bf16_f32 v48, v48, v49
	v_cvt_pk_bf16_f32 v50, v50, v51
	v_cvt_pk_bf16_f32 v52, v52, v53
	v_cvt_pk_bf16_f32 v54, v54, v55
	v_and_b32_e32 v121, s7, v48
	v_lshlrev_b32_e32 v120, 16, v48
	v_and_b32_e32 v123, s7, v50
	v_lshlrev_b32_e32 v122, 16, v50
	v_and_b32_e32 v125, s7, v52
	v_lshlrev_b32_e32 v124, 16, v52
	v_and_b32_e32 v127, s7, v54
	v_lshlrev_b32_e32 v126, 16, v54
	v_pk_fma_f32 v[56:57], v[8:9], v[32:33], 0 op_sel_hi:[1,1,0]
	v_pk_fma_f32 v[58:59], v[10:11], v[34:35], 0 op_sel_hi:[1,1,0]
	v_pk_fma_f32 v[60:61], v[12:13], v[36:37], 0 op_sel_hi:[1,1,0]
	v_pk_fma_f32 v[62:63], v[14:15], v[38:39], 0 op_sel_hi:[1,1,0]
	v_lshlrev_b32_e32 v48, 16, v128
	v_and_b32_e32 v49, s7, v128
	v_lshlrev_b32_e32 v50, 16, v129
	v_and_b32_e32 v51, s7, v129
	v_lshlrev_b32_e32 v52, 16, v130
	v_and_b32_e32 v53, s7, v130
	v_lshlrev_b32_e32 v54, 16, v131
	v_and_b32_e32 v55, s7, v131
	v_pk_fma_f32 v[56:57], v[16:17], v[40:41], v[56:57]
	v_pk_fma_f32 v[58:59], v[18:19], v[42:43], v[58:59]
	v_pk_fma_f32 v[60:61], v[20:21], v[44:45], v[60:61]
	v_pk_fma_f32 v[62:63], v[22:23], v[46:47], v[62:63]
	v_pk_fma_f32 v[56:57], v[24:25], v[120:121], v[56:57]
	v_pk_fma_f32 v[58:59], v[26:27], v[122:123], v[58:59]
	v_pk_fma_f32 v[60:61], v[28:29], v[124:125], v[60:61]
	v_pk_fma_f32 v[62:63], v[30:31], v[126:127], v[62:63]
	v_pk_mul_f32 v[48:49], v[56:57], v[48:49]
	v_pk_mul_f32 v[50:51], v[58:59], v[50:51]
	v_pk_mul_f32 v[52:53], v[60:61], v[52:53]
	v_pk_mul_f32 v[54:55], v[62:63], v[54:55]
	v_cvt_pk_bf16_f32 v64, v48, v49
	v_cvt_pk_bf16_f32 v65, v50, v51
	v_cvt_pk_bf16_f32 v66, v52, v53
	v_cvt_pk_bf16_f32 v67, v54, v55
	global_store_dwordx4 v1, v[64:67], s[18:19]
	s_add_u32 s18, s18, 0x800
	s_addc_u32 s19, s19, 0
	v_lshlrev_b32_e32 v48, 16, v132
	v_and_b32_e32 v49, s7, v132
	v_lshlrev_b32_e32 v56, 16, v136
	v_and_b32_e32 v57, s7, v136
	v_lshlrev_b32_e32 v50, 16, v133
	v_and_b32_e32 v51, s7, v133
	v_lshlrev_b32_e32 v58, 16, v137
	v_and_b32_e32 v59, s7, v137
	v_lshlrev_b32_e32 v52, 16, v134
	v_and_b32_e32 v53, s7, v134
	v_lshlrev_b32_e32 v60, 16, v138
	v_and_b32_e32 v61, s7, v138
	v_lshlrev_b32_e32 v54, 16, v135
	v_and_b32_e32 v55, s7, v135
	v_lshlrev_b32_e32 v62, 16, v139
	v_and_b32_e32 v63, s7, v139
	v_pk_mul_f32 v[48:49], v[56:57], v[48:49]
	v_pk_mul_f32 v[50:51], v[58:59], v[50:51]
	v_pk_mul_f32 v[52:53], v[60:61], v[52:53]
	v_pk_mul_f32 v[54:55], v[62:63], v[54:55]
	v_cvt_pk_bf16_f32 v48, v48, v49
	v_cvt_pk_bf16_f32 v50, v50, v51
	v_cvt_pk_bf16_f32 v52, v52, v53
	v_cvt_pk_bf16_f32 v54, v54, v55
	v_and_b32_e32 v133, s7, v48
	v_lshlrev_b32_e32 v132, 16, v48
	v_and_b32_e32 v135, s7, v50
	v_lshlrev_b32_e32 v134, 16, v50
	v_and_b32_e32 v137, s7, v52
	v_lshlrev_b32_e32 v136, 16, v52
	v_and_b32_e32 v139, s7, v54
	v_lshlrev_b32_e32 v138, 16, v54
	v_pk_fma_f32 v[56:57], v[8:9], v[40:41], 0 op_sel_hi:[1,1,0]
	v_pk_fma_f32 v[58:59], v[10:11], v[42:43], 0 op_sel_hi:[1,1,0]
	v_pk_fma_f32 v[60:61], v[12:13], v[44:45], 0 op_sel_hi:[1,1,0]
	v_pk_fma_f32 v[62:63], v[14:15], v[46:47], 0 op_sel_hi:[1,1,0]
	v_lshlrev_b32_e32 v48, 16, v140
	v_and_b32_e32 v49, s7, v140
	v_lshlrev_b32_e32 v50, 16, v141
	v_and_b32_e32 v51, s7, v141
	v_lshlrev_b32_e32 v52, 16, v142
	v_and_b32_e32 v53, s7, v142
	v_lshlrev_b32_e32 v54, 16, v143
	v_and_b32_e32 v55, s7, v143
	v_pk_fma_f32 v[56:57], v[16:17], v[120:121], v[56:57]
	v_pk_fma_f32 v[58:59], v[18:19], v[122:123], v[58:59]
	v_pk_fma_f32 v[60:61], v[20:21], v[124:125], v[60:61]
	v_pk_fma_f32 v[62:63], v[22:23], v[126:127], v[62:63]
	v_pk_fma_f32 v[56:57], v[24:25], v[132:133], v[56:57]
	v_pk_fma_f32 v[58:59], v[26:27], v[134:135], v[58:59]
	v_pk_fma_f32 v[60:61], v[28:29], v[136:137], v[60:61]
	v_pk_fma_f32 v[62:63], v[30:31], v[138:139], v[62:63]
	v_pk_mul_f32 v[48:49], v[56:57], v[48:49]
	v_pk_mul_f32 v[50:51], v[58:59], v[50:51]
	v_pk_mul_f32 v[52:53], v[60:61], v[52:53]
	v_pk_mul_f32 v[54:55], v[62:63], v[54:55]
	v_cvt_pk_bf16_f32 v68, v48, v49
	v_cvt_pk_bf16_f32 v69, v50, v51
	v_cvt_pk_bf16_f32 v70, v52, v53
	v_cvt_pk_bf16_f32 v71, v54, v55
	global_store_dwordx4 v1, v[68:71], s[18:19]
	s_add_u32 s18, s18, 0x800
	s_addc_u32 s19, s19, 0
	v_lshlrev_b32_e32 v48, 16, v144
	v_and_b32_e32 v49, s7, v144
	v_lshlrev_b32_e32 v56, 16, v148
	v_and_b32_e32 v57, s7, v148
	v_lshlrev_b32_e32 v50, 16, v145
	v_and_b32_e32 v51, s7, v145
	v_lshlrev_b32_e32 v58, 16, v149
	v_and_b32_e32 v59, s7, v149
	v_lshlrev_b32_e32 v52, 16, v146
	v_and_b32_e32 v53, s7, v146
	v_lshlrev_b32_e32 v60, 16, v150
	v_and_b32_e32 v61, s7, v150
	v_lshlrev_b32_e32 v54, 16, v147
	v_and_b32_e32 v55, s7, v147
	v_lshlrev_b32_e32 v62, 16, v151
	v_and_b32_e32 v63, s7, v151
	v_pk_mul_f32 v[48:49], v[56:57], v[48:49]
	v_pk_mul_f32 v[50:51], v[58:59], v[50:51]
	v_pk_mul_f32 v[52:53], v[60:61], v[52:53]
	v_pk_mul_f32 v[54:55], v[62:63], v[54:55]
	v_cvt_pk_bf16_f32 v48, v48, v49
	v_cvt_pk_bf16_f32 v50, v50, v51
	v_cvt_pk_bf16_f32 v52, v52, v53
	v_cvt_pk_bf16_f32 v54, v54, v55
	v_and_b32_e32 v33, s7, v48
	v_lshlrev_b32_e32 v32, 16, v48
	v_and_b32_e32 v35, s7, v50
	v_lshlrev_b32_e32 v34, 16, v50
	v_and_b32_e32 v37, s7, v52
	v_lshlrev_b32_e32 v36, 16, v52
	v_and_b32_e32 v39, s7, v54
	v_lshlrev_b32_e32 v38, 16, v54
	v_pk_fma_f32 v[56:57], v[8:9], v[120:121], 0 op_sel_hi:[1,1,0]
	v_pk_fma_f32 v[58:59], v[10:11], v[122:123], 0 op_sel_hi:[1,1,0]
	v_pk_fma_f32 v[60:61], v[12:13], v[124:125], 0 op_sel_hi:[1,1,0]
	v_pk_fma_f32 v[62:63], v[14:15], v[126:127], 0 op_sel_hi:[1,1,0]
	v_lshlrev_b32_e32 v48, 16, v152
	v_and_b32_e32 v49, s7, v152
	v_lshlrev_b32_e32 v50, 16, v153
	v_and_b32_e32 v51, s7, v153
	v_lshlrev_b32_e32 v52, 16, v154
	v_and_b32_e32 v53, s7, v154
	v_lshlrev_b32_e32 v54, 16, v155
	v_and_b32_e32 v55, s7, v155
	v_pk_fma_f32 v[56:57], v[16:17], v[132:133], v[56:57]
	v_pk_fma_f32 v[58:59], v[18:19], v[134:135], v[58:59]
	v_pk_fma_f32 v[60:61], v[20:21], v[136:137], v[60:61]
	v_pk_fma_f32 v[62:63], v[22:23], v[138:139], v[62:63]
	v_pk_fma_f32 v[56:57], v[24:25], v[32:33], v[56:57]
	v_pk_fma_f32 v[58:59], v[26:27], v[34:35], v[58:59]
	v_pk_fma_f32 v[60:61], v[28:29], v[36:37], v[60:61]
	v_pk_fma_f32 v[62:63], v[30:31], v[38:39], v[62:63]
	v_pk_mul_f32 v[48:49], v[56:57], v[48:49]
	v_pk_mul_f32 v[50:51], v[58:59], v[50:51]
	v_pk_mul_f32 v[52:53], v[60:61], v[52:53]
	v_pk_mul_f32 v[54:55], v[62:63], v[54:55]
	v_cvt_pk_bf16_f32 v64, v48, v49
	v_cvt_pk_bf16_f32 v65, v50, v51
	v_cvt_pk_bf16_f32 v66, v52, v53
	v_cvt_pk_bf16_f32 v67, v54, v55
	global_store_dwordx4 v1, v[64:67], s[18:19]
	s_add_u32 s18, s18, 0x800
	s_addc_u32 s19, s19, 0
	v_lshlrev_b32_e32 v48, 16, v156
	v_and_b32_e32 v49, s7, v156
	v_lshlrev_b32_e32 v56, 16, v160
	v_and_b32_e32 v57, s7, v160
	v_lshlrev_b32_e32 v50, 16, v157
	v_and_b32_e32 v51, s7, v157
	v_lshlrev_b32_e32 v58, 16, v161
	v_and_b32_e32 v59, s7, v161
	v_lshlrev_b32_e32 v52, 16, v158
	v_and_b32_e32 v53, s7, v158
	v_lshlrev_b32_e32 v60, 16, v162
	v_and_b32_e32 v61, s7, v162
	v_lshlrev_b32_e32 v54, 16, v159
	v_and_b32_e32 v55, s7, v159
	v_lshlrev_b32_e32 v62, 16, v163
	v_and_b32_e32 v63, s7, v163
	v_pk_mul_f32 v[48:49], v[56:57], v[48:49]
	v_pk_mul_f32 v[50:51], v[58:59], v[50:51]
	v_pk_mul_f32 v[52:53], v[60:61], v[52:53]
	v_pk_mul_f32 v[54:55], v[62:63], v[54:55]
	v_cvt_pk_bf16_f32 v48, v48, v49
	v_cvt_pk_bf16_f32 v50, v50, v51
	v_cvt_pk_bf16_f32 v52, v52, v53
	v_cvt_pk_bf16_f32 v54, v54, v55
	v_and_b32_e32 v41, s7, v48
	v_lshlrev_b32_e32 v40, 16, v48
	v_and_b32_e32 v43, s7, v50
	v_lshlrev_b32_e32 v42, 16, v50
	v_and_b32_e32 v45, s7, v52
	v_lshlrev_b32_e32 v44, 16, v52
	v_and_b32_e32 v47, s7, v54
	v_lshlrev_b32_e32 v46, 16, v54
	v_pk_fma_f32 v[56:57], v[8:9], v[132:133], 0 op_sel_hi:[1,1,0]
	v_pk_fma_f32 v[58:59], v[10:11], v[134:135], 0 op_sel_hi:[1,1,0]
	v_pk_fma_f32 v[60:61], v[12:13], v[136:137], 0 op_sel_hi:[1,1,0]
	v_pk_fma_f32 v[62:63], v[14:15], v[138:139], 0 op_sel_hi:[1,1,0]
	v_lshlrev_b32_e32 v48, 16, v164
	v_and_b32_e32 v49, s7, v164
	v_lshlrev_b32_e32 v50, 16, v165
	v_and_b32_e32 v51, s7, v165
	v_lshlrev_b32_e32 v52, 16, v166
	v_and_b32_e32 v53, s7, v166
	v_lshlrev_b32_e32 v54, 16, v167
	v_and_b32_e32 v55, s7, v167
	v_pk_fma_f32 v[56:57], v[16:17], v[32:33], v[56:57]
	v_pk_fma_f32 v[58:59], v[18:19], v[34:35], v[58:59]
	v_pk_fma_f32 v[60:61], v[20:21], v[36:37], v[60:61]
	v_pk_fma_f32 v[62:63], v[22:23], v[38:39], v[62:63]
	v_pk_fma_f32 v[56:57], v[24:25], v[40:41], v[56:57]
	v_pk_fma_f32 v[58:59], v[26:27], v[42:43], v[58:59]
	v_pk_fma_f32 v[60:61], v[28:29], v[44:45], v[60:61]
	v_pk_fma_f32 v[62:63], v[30:31], v[46:47], v[62:63]
	v_pk_mul_f32 v[48:49], v[56:57], v[48:49]
	v_pk_mul_f32 v[50:51], v[58:59], v[50:51]
	v_pk_mul_f32 v[52:53], v[60:61], v[52:53]
	v_pk_mul_f32 v[54:55], v[62:63], v[54:55]
	v_cvt_pk_bf16_f32 v68, v48, v49
	v_cvt_pk_bf16_f32 v69, v50, v51
	v_cvt_pk_bf16_f32 v70, v52, v53
	v_cvt_pk_bf16_f32 v71, v54, v55
	global_store_dwordx4 v1, v[68:71], s[18:19]
	s_add_u32 s18, s18, 0x800
	s_addc_u32 s19, s19, 0
	s_add_i32 s6, s6, -1
	s_cmp_eq_u32 s6, 0
	s_cbranch_scc1 .Lsc_done
	global_load_dwordx4 v[120:123], v0, s[2:3]
	global_load_dwordx4 v[124:127], v0, s[2:3] offset:2048
	global_load_dwordx4 v[128:131], v0, s[2:3] offset:-2048
	s_add_u32 s2, s2, 0x1800
	s_addc_u32 s3, s3, 0
	global_load_dwordx4 v[132:135], v0, s[2:3]
	global_load_dwordx4 v[136:139], v0, s[2:3] offset:2048
	global_load_dwordx4 v[140:143], v0, s[2:3] offset:-2048
	s_add_u32 s2, s2, 0x1800
	s_addc_u32 s3, s3, 0
	global_load_dwordx4 v[144:147], v0, s[2:3]
	global_load_dwordx4 v[148:151], v0, s[2:3] offset:2048
	global_load_dwordx4 v[152:155], v0, s[2:3] offset:-2048
	s_add_u32 s2, s2, 0x1800
	s_addc_u32 s3, s3, 0
	global_load_dwordx4 v[156:159], v0, s[2:3]
	global_load_dwordx4 v[160:163], v0, s[2:3] offset:2048
	global_load_dwordx4 v[164:167], v0, s[2:3] offset:-2048
	s_add_u32 s2, s2, 0x1800
	s_addc_u32 s3, s3, 0
	s_waitcnt vmcnt(16)
	s_branch .Lsc_loop
.Lsc_done:
	s_getreg_b32 s2, hwreg(HW_REG_XCC_ID, 0, 4)
	s_waitcnt vmcnt(0)
	s_barrier
	s_mov_b64 s[0:1], exec
	v_readlane_b32 s6, v253, 10
	v_readlane_b32 s7, v253, 11
	s_and_b64 s[6:7], s[0:1], s[6:7]
	s_mov_b64 exec, s[6:7]
	s_cbranch_execz .LBB0_1004
	s_add_i32 s3, 0, 0x22fe0
	v_mov_b32_e32 v0, s3
	s_add_i32 s3, 0, 0x22fe4
	s_waitcnt vmcnt(0) expcnt(0) lgkmcnt(0)
	ds_read_b32 v1, v0
	v_mov_b32_e32 v0, s3
	ds_read_b32 v0, v0
	s_mov_b64 s[6:7], exec
	s_lshl_b32 s2, s2, 8
	s_and_b32 s2, s2, 0xf00
	v_readlane_b32 s8, v253, 8
	v_mbcnt_lo_u32_b32 v2, s6, 0
	v_readlane_b32 s9, v253, 9
	s_add_u32 s2, s8, s2
	v_mbcnt_hi_u32_b32 v2, s7, v2
	s_addc_u32 s3, s9, 0
	v_cmp_eq_u32_e32 vcc, 0, v2
	s_and_saveexec_b64 s[8:9], vcc
	s_cbranch_execz .LBB0_984
	s_bcnt1_i32_b64 s6, s[6:7]
	v_mov_b32_e32 v3, 0x1000
	v_mov_b32_e32 v4, s6
	global_atomic_add v3, v3, v4, s[2:3] offset:1024 sc0
.LBB0_984:
	s_or_b64 exec, exec, s[8:9]
	s_waitcnt lgkmcnt(1)
	v_cvt_f32_u32_e32 v4, v1
	s_waitcnt vmcnt(0)
	v_readfirstlane_b32 s6, v3
	v_sub_u32_e32 v3, 0, v1
	v_rcp_iflag_f32_e32 v4, v4
	v_add_u32_e32 v5, s6, v2
	v_mul_f32_e32 v4, 0x4f7ffffe, v4
	v_cvt_u32_f32_e32 v4, v4
	v_mul_lo_u32 v2, v3, v4
	v_mul_hi_u32 v2, v4, v2
	v_add_u32_e32 v2, v4, v2
	v_mul_hi_u32 v2, v5, v2
	v_mul_lo_u32 v3, v2, v1
	v_sub_u32_e32 v3, v5, v3
	v_add_u32_e32 v4, 1, v2
	v_cmp_ge_u32_e32 vcc, v3, v1
	s_nop 1
	v_cndmask_b32_e32 v2, v2, v4, vcc
	v_sub_u32_e32 v4, v3, v1
	v_cndmask_b32_e32 v3, v3, v4, vcc
	v_add_u32_e32 v4, 1, v2
	v_cmp_ge_u32_e32 vcc, v3, v1
	v_add_u32_e32 v3, 1, v5
	s_nop 0
	v_cndmask_b32_e32 v2, v2, v4, vcc
	v_mul_lo_u32 v4, v1, v2
	v_add_u32_e32 v1, v4, v1
	v_cmp_ne_u32_e32 vcc, v3, v1
	s_and_saveexec_b64 s[6:7], vcc
	s_xor_b64 s[6:7], exec, s[6:7]
	s_cbranch_execz .LBB0_989
	s_waitcnt lgkmcnt(0)
	v_mov_b32_e32 v0, 0x2000
	global_load_dword v0, v0, s[2:3] offset:1024 sc1
	s_add_u32 s8, s2, 0x2400
	s_addc_u32 s9, s3, 0
	s_waitcnt vmcnt(0)
	v_cmp_eq_u32_e32 vcc, v0, v2
	s_and_saveexec_b64 s[18:19], vcc
	s_cbranch_execz .LBB0_988
	s_mov_b64 s[20:21], 0
	v_mov_b32_e32 v0, 0
